# attention: next item's Q and first K/V tile prefetched during the current item's last tile, epilogue gate values prefetched at each wave's last active tile
# speedup vs baseline: 1.0222x; 1.0140x over previous
.LBB0_316:
	s_barrier
	v_readlane_b32 s4, v251, 48
	v_readlane_b32 s34, v253, 15
	v_mbcnt_lo_u32_b32 v0, -1, 0
	v_mbcnt_hi_u32_b32 v0, -1, v0
	s_lshr_b32 s36, s4, 2
	s_and_b32 s31, s4, 3
	s_lshr_b32 s29, s36, 3
	s_and_b32 s30, s36, 7
	s_lshr_b32 s34, s34, 6
	s_lshr_b32 s35, s34, 2
	v_and_b32_e32 v240, 31, v0
	v_lshrrev_b32_e32 v241, 5, v0
	v_lshl_add_u32 v247, s34, 6, v0
	v_lshrrev_b32_e32 v248, 4, v247
	v_and_b32_e32 v249, 15, v247
	v_lshlrev_b32_e32 v220, 11, v248
	v_lshl_add_u32 v220, v249, 4, v220
	v_mul_u32_u24_e32 v225, 0x190, v248
	v_lshl_add_u32 v225, v249, 4, v225
	v_lshrrev_b32_e32 v248, 3, v247
	v_and_b32_e32 v249, 7, v247
	v_lshlrev_b32_e32 v221, 7, v248
	v_lshl_add_u32 v221, v249, 4, v221
	v_mul_u32_u24_e32 v226, 0x190, v248
	v_lshl_add_u32 v226, v249, 4, v226
	v_add_u32_e32 v226, 0x100, v226
	v_mul_u32_u24_e32 v222, 0x8200, v248
	v_lshl_add_u32 v222, v249, 4, v222
	v_mul_u32_u24_e32 v227, 0x88, v248
	v_lshl_add_u32 v227, v249, 4, v227
	v_add_u32_e32 v227, 0x12c00, v227
	v_add_u32_e32 v228, 0x2200, v227
	v_lshlrev_b32_e32 v223, 5, v0
	v_lshlrev_b32_e32 v224, 2, v0
	v_add_u32_e32 v229, 0x1f800, v224
	v_mul_u32_u24_e32 v230, 0x190, v240
	v_lshl_add_u32 v230, v241, 4, v230
	v_mul_u32_u24_e32 v231, 0x88, v240
	v_lshl_add_u32 v231, v241, 3, v231
	v_add_u32_e32 v231, 0x12c00, v231
	v_lshlrev_b32_e32 v232, 4, v241
	v_add_u32_e32 v232, 0x1f800, v232
	v_xor_b32_e32 v233, 32, v0
	v_lshlrev_b32_e32 v233, 2, v233
	v_mov_b32_e32 v238, 0xf149f2ca
	s_mov_b32 s26, 0
	s_mul_i32 s38, s29, 0x810
	s_mul_i32 s36, s30, 0x180
	s_add_u32 s40, s50, s36
	s_addc_u32 s41, s51, 0
	s_lshl_b32 s36, s30, 8
	s_add_u32 s36, s36, 0xc380000
	s_add_u32 s6, s48, s36
	s_addc_u32 s7, s49, 0
.Lat_item:
	s_sub_i32 s36, 8, s31
	s_add_i32 s37, s31, 1
	s_cmp_eq_u32 s26, 0
	s_cselect_b32 s36, s36, s37
	s_cmp_eq_u32 s26, 2
	s_cselect_b32 s36, 0, s36
	s_lshl_b32 s27, s36, 8
	s_sub_i32 s27, s27, 0xf0
	s_cmp_eq_u32 s36, 0
	s_cselect_b32 s27, 0, s27
	s_cselect_b32 s28, 16, 0x100
	s_add_i32 s23, s27, s28
	s_add_i32 s23, s23, 63
	s_lshr_b32 s23, s23, 6
	s_lshl_b32 s65, s34, 5
	s_add_i32 s64, s65, s27
	s_add_i32 s25, s64, 31
	s_lshr_b32 s25, s25, 6
	s_cmp_lt_u32 s65, s28
	s_cselect_b32 s25, s25, -1
	v_add_u32_e32 v234, s64, v240
	v_lshlrev_b32_e32 v0, 2, v241
	v_sub_u32_e32 v239, v234, v0
	s_cmp_lg_u32 s26, 0
	s_cbranch_scc1 .Lat_item_nofetch
	s_mov_b32 s4, s27
	s_lshl_b32 s65, s34, 5
	s_add_i32 s5, s65, s4
	v_add_u32_e32 v0, s5, v240
	v_min_u32_e32 v0, 0x80f, v0
	v_add_u32_e32 v0, s38, v0
	s_movk_i32 s39, 0xc00
	v_mul_lo_u32 v247, v0, s39
	v_lshl_add_u32 v247, v241, 4, v247
	v_lshlrev_b32_e32 v242, 5, v0
	global_load_dwordx4 v[98:101], v247, s[40:41]
	global_load_dwordx4 v[102:105], v247, s[40:41] offset:32
	global_load_dwordx4 v[106:109], v247, s[40:41] offset:64
	global_load_dwordx4 v[110:113], v247, s[40:41] offset:96
	global_load_dwordx4 v[114:117], v247, s[40:41] offset:128
	global_load_dwordx4 v[118:121], v247, s[40:41] offset:160
	global_load_dwordx4 v[122:125], v247, s[40:41] offset:192
	global_load_dwordx4 v[126:129], v247, s[40:41] offset:224
	global_load_dwordx4 v[130:133], v247, s[40:41] offset:256
	global_load_dwordx4 v[134:137], v247, s[40:41] offset:288
	global_load_dwordx4 v[138:141], v247, s[40:41] offset:320
	global_load_dwordx4 v[142:145], v247, s[40:41] offset:352
	s_lshl_b32 s36, s30, 2
	s_add_u32 s36, s36, 0x1507a400
	s_add_u32 s36, s48, s36
	s_addc_u32 s37, s49, 0
	global_load_dword v249, v242, s[36:37]
	s_lshl_b32 s73, s38, 11
	s_add_u32 s72, s73, 0x10480000
	s_lshl_b32 s73, s30, 8
	s_add_u32 s72, s72, s73
	s_add_u32 s8, s48, s72
	s_addc_u32 s9, s49, 0
	s_add_u32 s10, s8, 0x10000
	s_addc_u32 s11, s9, 0
	s_lshl_b32 s73, s38, 7
	s_add_u32 s72, s73, 0x14da0000
	s_add_u32 s12, s48, s72
	s_addc_u32 s13, s49, 0
	s_mul_i32 s73, s30, 0x410000
	s_lshl_b32 s72, s38, 1
	s_add_u32 s72, s72, s73
	s_add_u32 s72, s72, 0x12500000
	s_add_u32 s14, s48, s72
	s_addc_u32 s15, s49, 0
	s_add_u32 s16, s14, 0x208000
	s_addc_u32 s17, s15, 0
	s_lshl_b32 s73, s38, 5
	s_add_u32 s72, s73, 0x150fc400
	s_lshl_b32 s73, s30, 2
	s_add_u32 s72, s72, s73
	s_add_u32 s18, s48, s72
	s_addc_u32 s19, s49, 0
	s_lshl_b32 s73, s38, 2
	s_add_u32 s72, s73, 0x1506a000
	s_add_u32 s20, s48, s72
	s_addc_u32 s21, s49, 0
	global_load_dwordx4 v[198:201], v220, s[8:9]
	global_load_dwordx4 v[202:205], v220, s[10:11]
	global_load_dwordx4 v[206:209], v221, s[12:13]
	global_load_dwordx4 v[210:213], v222, s[14:15]
	global_load_dwordx4 v[214:217], v222, s[16:17]
	s_cmp_lg_u32 s34, 0
	s_cbranch_scc1 .Lat_nosq1
	global_load_dword v218, v223, s[18:19]
	global_load_dword v219, v224, s[20:21]
.Lat_nosq1:
.Lat_item_nofetch:
	v_mov_b32_e32 v2, 0
	v_mov_b32_e32 v3, 0
	v_mov_b32_e32 v4, 0
	v_mov_b32_e32 v5, 0
	v_mov_b32_e32 v6, 0
	v_mov_b32_e32 v7, 0
	v_mov_b32_e32 v8, 0
	v_mov_b32_e32 v9, 0
	v_mov_b32_e32 v10, 0
	v_mov_b32_e32 v11, 0
	v_mov_b32_e32 v12, 0
	v_mov_b32_e32 v13, 0
	v_mov_b32_e32 v14, 0
	v_mov_b32_e32 v15, 0
	v_mov_b32_e32 v16, 0
	v_mov_b32_e32 v17, 0
	v_mov_b32_e32 v18, 0
	v_mov_b32_e32 v19, 0
	v_mov_b32_e32 v20, 0
	v_mov_b32_e32 v21, 0
	v_mov_b32_e32 v22, 0
	v_mov_b32_e32 v23, 0
	v_mov_b32_e32 v24, 0
	v_mov_b32_e32 v25, 0
	v_mov_b32_e32 v26, 0
	v_mov_b32_e32 v27, 0
	v_mov_b32_e32 v28, 0
	v_mov_b32_e32 v29, 0
	v_mov_b32_e32 v30, 0
	v_mov_b32_e32 v31, 0
	v_mov_b32_e32 v32, 0
	v_mov_b32_e32 v33, 0
	v_mov_b32_e32 v34, 0
	v_mov_b32_e32 v35, 0
	v_mov_b32_e32 v36, 0
	v_mov_b32_e32 v37, 0
	v_mov_b32_e32 v38, 0
	v_mov_b32_e32 v39, 0
	v_mov_b32_e32 v40, 0
	v_mov_b32_e32 v41, 0
	v_mov_b32_e32 v42, 0
	v_mov_b32_e32 v43, 0
	v_mov_b32_e32 v44, 0
	v_mov_b32_e32 v45, 0
	v_mov_b32_e32 v46, 0
	v_mov_b32_e32 v47, 0
	v_mov_b32_e32 v48, 0
	v_mov_b32_e32 v49, 0
	v_mov_b32_e32 v50, 0
	v_mov_b32_e32 v51, 0
	v_mov_b32_e32 v52, 0
	v_mov_b32_e32 v53, 0
	v_mov_b32_e32 v54, 0
	v_mov_b32_e32 v55, 0
	v_mov_b32_e32 v56, 0
	v_mov_b32_e32 v57, 0
	v_mov_b32_e32 v58, 0
	v_mov_b32_e32 v59, 0
	v_mov_b32_e32 v60, 0
	v_mov_b32_e32 v61, 0
	v_mov_b32_e32 v62, 0
	v_mov_b32_e32 v63, 0
	v_mov_b32_e32 v64, 0
	v_mov_b32_e32 v65, 0
	v_mov_b32_e32 v236, v238
	v_mov_b32_e32 v237, 0
	s_mov_b32 s36, 0
	s_mov_b32 s37, 0
	s_mov_b32 s39, 0

.Lat_nosc2:
	v_mov_b32_e32 v242, 0x358637bd
	v_fmamk_f32 v235, v249, 0x3baaaaab, v242
	v_rsq_f32_e32 v235, v235
	s_nop 0
	v_mul_f32_e32 v235, 0x3dd53b95, v235
	s_cmp_lt_u32 s23, 2
	s_cbranch_scc1 .Lat_no_t1
	s_add_u32 s8, s8, 0x20000
	s_addc_u32 s9, s9, 0
	s_add_u32 s10, s10, 0x20000
	s_addc_u32 s11, s11, 0
	s_add_u32 s12, s12, 0x2000
	s_addc_u32 s13, s13, 0
	s_add_u32 s14, s14, 0x80
	s_addc_u32 s15, s15, 0
	s_add_u32 s16, s16, 0x80
	s_addc_u32 s17, s17, 0
	s_add_u32 s18, s18, 0x800
	s_addc_u32 s19, s19, 0
	s_add_u32 s20, s20, 0x100
	s_addc_u32 s21, s21, 0
	global_load_dwordx4 v[198:201], v220, s[8:9]
	global_load_dwordx4 v[202:205], v220, s[10:11]
	global_load_dwordx4 v[206:209], v221, s[12:13]
	global_load_dwordx4 v[210:213], v222, s[14:15]
	global_load_dwordx4 v[214:217], v222, s[16:17]
	s_cmp_lg_u32 s34, 0
	s_cbranch_scc1 .Lat_nosq3
	global_load_dword v218, v223, s[18:19]
	global_load_dword v219, v224, s[20:21]

.Lat_x_nopv:
	s_cmp_gt_i32 s22, s25
	s_cbranch_scc1 .Lat_x_noqk
	ds_read_b128 v[146:149], v0 offset:128
	ds_read_b128 v[150:153], v0 offset:12928
	s_waitcnt lgkmcnt(8)
	v_mfma_f32_32x32x16_bf16 v[66:81], v[162:165], v[98:101], 0
	v_mfma_f32_32x32x16_bf16 v[82:97], v[166:169], v[98:101], 0
	ds_read_b128 v[154:157], v0 offset:160
	ds_read_b128 v[158:161], v0 offset:12960
	s_waitcnt lgkmcnt(8)
	v_mfma_f32_32x32x16_bf16 v[66:81], v[170:173], v[102:105], v[66:81]
	v_mfma_f32_32x32x16_bf16 v[82:97], v[174:177], v[102:105], v[82:97]
	ds_read_b128 v[162:165], v0 offset:192
	ds_read_b128 v[166:169], v0 offset:12992
	s_waitcnt lgkmcnt(8)
	v_mfma_f32_32x32x16_bf16 v[66:81], v[178:181], v[106:109], v[66:81]
	v_mfma_f32_32x32x16_bf16 v[82:97], v[182:185], v[106:109], v[82:97]
	ds_read_b128 v[170:173], v0 offset:224
	ds_read_b128 v[174:177], v0 offset:13024
	s_waitcnt lgkmcnt(8)
	v_mfma_f32_32x32x16_bf16 v[66:81], v[186:189], v[110:113], v[66:81]
	v_mfma_f32_32x32x16_bf16 v[82:97], v[190:193], v[110:113], v[82:97]
	ds_read_b128 v[178:181], v0 offset:256
	ds_read_b128 v[182:185], v0 offset:13056
	s_waitcnt lgkmcnt(8)
	v_mfma_f32_32x32x16_bf16 v[66:81], v[146:149], v[114:117], v[66:81]
	v_mfma_f32_32x32x16_bf16 v[82:97], v[150:153], v[114:117], v[82:97]
	ds_read_b128 v[186:189], v0 offset:288
	ds_read_b128 v[190:193], v0 offset:13088
	s_waitcnt lgkmcnt(8)
	v_mfma_f32_32x32x16_bf16 v[66:81], v[154:157], v[118:121], v[66:81]
	v_mfma_f32_32x32x16_bf16 v[82:97], v[158:161], v[118:121], v[82:97]
	ds_read_b128 v[146:149], v0 offset:320
	ds_read_b128 v[150:153], v0 offset:13120
	s_waitcnt lgkmcnt(8)
	v_mfma_f32_32x32x16_bf16 v[66:81], v[162:165], v[122:125], v[66:81]
	v_mfma_f32_32x32x16_bf16 v[82:97], v[166:169], v[122:125], v[82:97]
	ds_read_b128 v[154:157], v0 offset:352
	ds_read_b128 v[158:161], v0 offset:13152
	s_waitcnt lgkmcnt(8)
	v_mfma_f32_32x32x16_bf16 v[66:81], v[170:173], v[126:129], v[66:81]
	v_mfma_f32_32x32x16_bf16 v[82:97], v[174:177], v[126:129], v[82:97]
	s_waitcnt lgkmcnt(6)
	v_mfma_f32_32x32x16_bf16 v[66:81], v[178:181], v[130:133], v[66:81]
	v_mfma_f32_32x32x16_bf16 v[82:97], v[182:185], v[130:133], v[82:97]
	s_waitcnt lgkmcnt(4)
	v_mfma_f32_32x32x16_bf16 v[66:81], v[186:189], v[134:137], v[66:81]
	v_mfma_f32_32x32x16_bf16 v[82:97], v[190:193], v[134:137], v[82:97]
	s_waitcnt lgkmcnt(2)
	v_mfma_f32_32x32x16_bf16 v[66:81], v[146:149], v[138:141], v[66:81]
	v_mfma_f32_32x32x16_bf16 v[82:97], v[150:153], v[138:141], v[82:97]
	s_waitcnt lgkmcnt(0)
	v_mfma_f32_32x32x16_bf16 v[66:81], v[154:157], v[142:145], v[66:81]
	v_mfma_f32_32x32x16_bf16 v[82:97], v[158:161], v[142:145], v[82:97]
	s_lshl_b32 s39, s24, 8
	v_add_u32_e32 v0, s39, v232
	ds_read_b128 v[162:165], v0
	ds_read_b128 v[166:169], v0 offset:32
	ds_read_b128 v[170:173], v0 offset:64
	ds_read_b128 v[174:177], v0 offset:96
	ds_read_b128 v[178:181], v0 offset:128
	ds_read_b128 v[182:185], v0 offset:160
	ds_read_b128 v[186:189], v0 offset:192
	ds_read_b128 v[190:193], v0 offset:224
	s_branch .Lat_x_pref

.Lat_x_pref:
	s_add_i32 s65, s22, 1
	s_cmp_lg_u32 s65, s23
	s_cbranch_scc1 .Lat_x_nopf
	s_cmp_eq_u32 s26, 2
	s_cbranch_scc1 .Lat_x_nopf
	s_cmp_eq_u32 s26, 0
	s_cbranch_scc1 .Lat_x_pf1
	s_cmp_lg_u32 s31, 0
	s_cbranch_scc1 .Lat_x_nopf
	s_mov_b32 s4, 0
	s_branch .Lat_x_pf
.Lat_x_pf1:
	s_lshl_b32 s4, s31, 8
	s_add_i32 s4, s4, 16
.Lat_x_pf:
	s_lshl_b32 s65, s34, 5
	s_add_i32 s5, s65, s4
	v_add_u32_e32 v0, s5, v240
	v_min_u32_e32 v0, 0x80f, v0
	v_add_u32_e32 v0, s38, v0
	s_movk_i32 s39, 0xc00
	v_mul_lo_u32 v247, v0, s39
	v_lshl_add_u32 v247, v241, 4, v247
	v_lshlrev_b32_e32 v242, 5, v0
	global_load_dwordx4 v[98:101], v247, s[40:41]
	global_load_dwordx4 v[102:105], v247, s[40:41] offset:32
	global_load_dwordx4 v[106:109], v247, s[40:41] offset:64
	global_load_dwordx4 v[110:113], v247, s[40:41] offset:96
	global_load_dwordx4 v[114:117], v247, s[40:41] offset:128
	global_load_dwordx4 v[118:121], v247, s[40:41] offset:160
	global_load_dwordx4 v[122:125], v247, s[40:41] offset:192
	global_load_dwordx4 v[126:129], v247, s[40:41] offset:224
	global_load_dwordx4 v[130:133], v247, s[40:41] offset:256
	global_load_dwordx4 v[134:137], v247, s[40:41] offset:288
	global_load_dwordx4 v[138:141], v247, s[40:41] offset:320
	global_load_dwordx4 v[142:145], v247, s[40:41] offset:352
	s_lshl_b32 s36, s30, 2
	s_add_u32 s36, s36, 0x1507a400
	s_add_u32 s36, s48, s36
	s_addc_u32 s37, s49, 0
	global_load_dword v249, v242, s[36:37]
	s_lshl_b32 s73, s38, 11
	s_add_u32 s72, s73, 0x10480000
	s_lshl_b32 s73, s30, 8
	s_add_u32 s72, s72, s73
	s_add_u32 s8, s48, s72
	s_addc_u32 s9, s49, 0
	s_add_u32 s10, s8, 0x10000
	s_addc_u32 s11, s9, 0
	s_lshl_b32 s73, s38, 7
	s_add_u32 s72, s73, 0x14da0000
	s_add_u32 s12, s48, s72
	s_addc_u32 s13, s49, 0
	s_mul_i32 s73, s30, 0x410000
	s_lshl_b32 s72, s38, 1
	s_add_u32 s72, s72, s73
	s_add_u32 s72, s72, 0x12500000
	s_add_u32 s14, s48, s72
	s_addc_u32 s15, s49, 0
	s_add_u32 s16, s14, 0x208000
	s_addc_u32 s17, s15, 0
	s_lshl_b32 s73, s38, 5
	s_add_u32 s72, s73, 0x150fc400
	s_lshl_b32 s73, s30, 2
	s_add_u32 s72, s72, s73
	s_add_u32 s18, s48, s72
	s_addc_u32 s19, s49, 0
	s_lshl_b32 s73, s38, 2
	s_add_u32 s72, s73, 0x1506a000
	s_add_u32 s20, s48, s72
	s_addc_u32 s21, s49, 0
	global_load_dwordx4 v[198:201], v220, s[8:9]
	global_load_dwordx4 v[202:205], v220, s[10:11]
	global_load_dwordx4 v[206:209], v221, s[12:13]
	global_load_dwordx4 v[210:213], v222, s[14:15]
	global_load_dwordx4 v[214:217], v222, s[16:17]
	s_cmp_lg_u32 s34, 0
	s_cbranch_scc1 .Lat_nosq6
	global_load_dword v218, v223, s[18:19]
	global_load_dword v219, v224, s[20:21]
.Lat_nosq6:
.Lat_x_nopf:
	s_barrier
	s_cmp_gt_i32 s22, s25
	s_cbranch_scc1 .Lat_y_done
	s_nop 7
	s_waitcnt lgkmcnt(0)
	v_mul_f32_e32 v66, v66, v162
	v_mul_f32_e32 v67, v67, v163
	v_mul_f32_e32 v68, v68, v164
	v_mul_f32_e32 v69, v69, v165
	v_mul_f32_e32 v70, v70, v166
	v_mul_f32_e32 v71, v71, v167
	v_mul_f32_e32 v72, v72, v168
	v_mul_f32_e32 v73, v73, v169
	v_mul_f32_e32 v74, v74, v170
	v_mul_f32_e32 v75, v75, v171
	v_mul_f32_e32 v76, v76, v172
	v_mul_f32_e32 v77, v77, v173
	v_mul_f32_e32 v78, v78, v174
	v_mul_f32_e32 v79, v79, v175
	v_mul_f32_e32 v80, v80, v176
	v_mul_f32_e32 v81, v81, v177
	v_mul_f32_e32 v82, v82, v178
	v_mul_f32_e32 v83, v83, v179
	v_mul_f32_e32 v84, v84, v180
	v_mul_f32_e32 v85, v85, v181
	v_mul_f32_e32 v86, v86, v182
	v_mul_f32_e32 v87, v87, v183
	v_mul_f32_e32 v88, v88, v184
	v_mul_f32_e32 v89, v89, v185
	v_mul_f32_e32 v90, v90, v186
	v_mul_f32_e32 v91, v91, v187
	v_mul_f32_e32 v92, v92, v188
	v_mul_f32_e32 v93, v93, v189
	v_mul_f32_e32 v94, v94, v190
	v_mul_f32_e32 v95, v95, v191
	v_mul_f32_e32 v96, v96, v192
	v_mul_f32_e32 v97, v97, v193
	s_cmp_lg_u32 s22, s25
	s_cbranch_scc1 .Lat_y_nogate
	v_add_u32_e32 v194, s38, v234
	v_lshlrev_b32_e32 v194, 11, v194
	v_lshl_add_u32 v194, v241, 3, v194
	global_load_dwordx2 v[162:163], v194, s[6:7] offset:0
	global_load_dwordx2 v[164:165], v194, s[6:7] offset:16
	global_load_dwordx2 v[166:167], v194, s[6:7] offset:32
	global_load_dwordx2 v[168:169], v194, s[6:7] offset:48
	global_load_dwordx2 v[170:171], v194, s[6:7] offset:64
	global_load_dwordx2 v[172:173], v194, s[6:7] offset:80
	global_load_dwordx2 v[174:175], v194, s[6:7] offset:96
	global_load_dwordx2 v[176:177], v194, s[6:7] offset:112
	global_load_dwordx2 v[178:179], v194, s[6:7] offset:128
	global_load_dwordx2 v[180:181], v194, s[6:7] offset:144
	global_load_dwordx2 v[182:183], v194, s[6:7] offset:160
	global_load_dwordx2 v[184:185], v194, s[6:7] offset:176
	global_load_dwordx2 v[186:187], v194, s[6:7] offset:192
	global_load_dwordx2 v[188:189], v194, s[6:7] offset:208
	global_load_dwordx2 v[190:191], v194, s[6:7] offset:224
	global_load_dwordx2 v[192:193], v194, s[6:7] offset:240
.Lat_y_nogate:
	s_lshl_b32 s65, s22, 6
	s_add_i32 s72, s65, 63
	s_cmp_le_i32 s72, s64
	s_cbranch_scc1 .Lat_y_nomask
	v_subrev_u32_e32 v242, s65, v239
	v_cmp_gt_i32_e32 vcc, 0, v242
	v_cmp_gt_i32_e64 s[36:37], 1, v242
	s_nop 0
	v_cndmask_b32_e32 v66, v66, v238, vcc
	v_cndmask_b32_e64 v67, v67, v238, s[36:37]
	v_cmp_gt_i32_e32 vcc, 2, v242
	v_cmp_gt_i32_e64 s[36:37], 3, v242
	s_nop 0
	v_cndmask_b32_e32 v68, v68, v238, vcc
	v_cndmask_b32_e64 v69, v69, v238, s[36:37]
	v_cmp_gt_i32_e32 vcc, 8, v242
	v_cmp_gt_i32_e64 s[36:37], 9, v242
	s_nop 0
	v_cndmask_b32_e32 v70, v70, v238, vcc
	v_cndmask_b32_e64 v71, v71, v238, s[36:37]
	v_cmp_gt_i32_e32 vcc, 10, v242
	v_cmp_gt_i32_e64 s[36:37], 11, v242
	s_nop 0
	v_cndmask_b32_e32 v72, v72, v238, vcc
	v_cndmask_b32_e64 v73, v73, v238, s[36:37]
	v_cmp_gt_i32_e32 vcc, 16, v242
	v_cmp_gt_i32_e64 s[36:37], 17, v242
	s_nop 0
	v_cndmask_b32_e32 v74, v74, v238, vcc
	v_cndmask_b32_e64 v75, v75, v238, s[36:37]
	v_cmp_gt_i32_e32 vcc, 18, v242
	v_cmp_gt_i32_e64 s[36:37], 19, v242
	s_nop 0
	v_cndmask_b32_e32 v76, v76, v238, vcc
	v_cndmask_b32_e64 v77, v77, v238, s[36:37]
	v_cmp_gt_i32_e32 vcc, 24, v242
	v_cmp_gt_i32_e64 s[36:37], 25, v242
	s_nop 0
	v_cndmask_b32_e32 v78, v78, v238, vcc
	v_cndmask_b32_e64 v79, v79, v238, s[36:37]
	v_cmp_gt_i32_e32 vcc, 26, v242
	v_cmp_gt_i32_e64 s[36:37], 27, v242
	s_nop 0
	v_cndmask_b32_e32 v80, v80, v238, vcc
	v_cndmask_b32_e64 v81, v81, v238, s[36:37]
	v_cmp_gt_i32_e32 vcc, 32, v242
	v_cmp_gt_i32_e64 s[36:37], 33, v242
	s_nop 0
	v_cndmask_b32_e32 v82, v82, v238, vcc
	v_cndmask_b32_e64 v83, v83, v238, s[36:37]
	v_cmp_gt_i32_e32 vcc, 34, v242
	v_cmp_gt_i32_e64 s[36:37], 35, v242
	s_nop 0
	v_cndmask_b32_e32 v84, v84, v238, vcc
	v_cndmask_b32_e64 v85, v85, v238, s[36:37]
	v_cmp_gt_i32_e32 vcc, 40, v242
	v_cmp_gt_i32_e64 s[36:37], 41, v242
	s_nop 0
	v_cndmask_b32_e32 v86, v86, v238, vcc
	v_cndmask_b32_e64 v87, v87, v238, s[36:37]
	v_cmp_gt_i32_e32 vcc, 42, v242
	v_cmp_gt_i32_e64 s[36:37], 43, v242
	s_nop 0
	v_cndmask_b32_e32 v88, v88, v238, vcc
	v_cndmask_b32_e64 v89, v89, v238, s[36:37]
	v_cmp_gt_i32_e32 vcc, 48, v242
	v_cmp_gt_i32_e64 s[36:37], 49, v242
	s_nop 0
	v_cndmask_b32_e32 v90, v90, v238, vcc
	v_cndmask_b32_e64 v91, v91, v238, s[36:37]
	v_cmp_gt_i32_e32 vcc, 50, v242
	v_cmp_gt_i32_e64 s[36:37], 51, v242
	s_nop 0
	v_cndmask_b32_e32 v92, v92, v238, vcc
	v_cndmask_b32_e64 v93, v93, v238, s[36:37]
	v_cmp_gt_i32_e32 vcc, 56, v242
	v_cmp_gt_i32_e64 s[36:37], 57, v242
	s_nop 0
	v_cndmask_b32_e32 v94, v94, v238, vcc
	v_cndmask_b32_e64 v95, v95, v238, s[36:37]
	v_cmp_gt_i32_e32 vcc, 58, v242
	v_cmp_gt_i32_e64 s[36:37], 59, v242
	s_nop 0
	v_cndmask_b32_e32 v96, v96, v238, vcc
	v_cndmask_b32_e64 v97, v97, v238, s[36:37]

.Lat_y_norescale:
	v_fma_f32 v66, v235, v66, -v195
	v_fma_f32 v67, v235, v67, -v195
	v_exp_f32_e32 v66, v66
	v_fma_f32 v68, v235, v68, -v195
	v_exp_f32_e32 v67, v67
	v_fma_f32 v69, v235, v69, -v195
	v_exp_f32_e32 v68, v68
	v_fma_f32 v70, v235, v70, -v195
	v_exp_f32_e32 v69, v69
	v_fma_f32 v71, v235, v71, -v195
	v_exp_f32_e32 v70, v70
	v_fma_f32 v72, v235, v72, -v195
	v_exp_f32_e32 v71, v71
	v_fma_f32 v73, v235, v73, -v195
	v_exp_f32_e32 v72, v72
	v_fma_f32 v74, v235, v74, -v195
	v_exp_f32_e32 v73, v73
	v_fma_f32 v75, v235, v75, -v195
	v_exp_f32_e32 v74, v74
	v_fma_f32 v76, v235, v76, -v195
	v_exp_f32_e32 v75, v75
	v_fma_f32 v77, v235, v77, -v195
	v_exp_f32_e32 v76, v76
	v_fma_f32 v78, v235, v78, -v195
	v_exp_f32_e32 v77, v77
	v_fma_f32 v79, v235, v79, -v195
	v_exp_f32_e32 v78, v78
	v_fma_f32 v80, v235, v80, -v195
	v_exp_f32_e32 v79, v79
	v_fma_f32 v81, v235, v81, -v195
	v_exp_f32_e32 v80, v80
	v_fma_f32 v82, v235, v82, -v195
	v_exp_f32_e32 v81, v81
	v_fma_f32 v83, v235, v83, -v195
	v_exp_f32_e32 v82, v82
	v_fma_f32 v84, v235, v84, -v195
	v_exp_f32_e32 v83, v83
	v_fma_f32 v85, v235, v85, -v195
	v_exp_f32_e32 v84, v84
	v_fma_f32 v86, v235, v86, -v195
	v_exp_f32_e32 v85, v85
	v_fma_f32 v87, v235, v87, -v195
	v_exp_f32_e32 v86, v86
	v_fma_f32 v88, v235, v88, -v195
	v_exp_f32_e32 v87, v87
	v_fma_f32 v89, v235, v89, -v195
	v_exp_f32_e32 v88, v88
	v_fma_f32 v90, v235, v90, -v195
	v_exp_f32_e32 v89, v89
	v_fma_f32 v91, v235, v91, -v195
	v_exp_f32_e32 v90, v90
	v_fma_f32 v92, v235, v92, -v195
	v_exp_f32_e32 v91, v91
	v_fma_f32 v93, v235, v93, -v195
	v_exp_f32_e32 v92, v92
	v_fma_f32 v94, v235, v94, -v195
	v_exp_f32_e32 v93, v93
	v_fma_f32 v95, v235, v95, -v195
	v_exp_f32_e32 v94, v94
	v_fma_f32 v96, v235, v96, -v195
	v_exp_f32_e32 v95, v95
	v_fma_f32 v97, v235, v97, -v195
	v_exp_f32_e32 v96, v96
	v_exp_f32_e32 v97, v97
	s_nop 0
	v_add_f32_e32 v243, v66, v70
	v_add_f32_e32 v244, v67, v71
	v_add_f32_e32 v245, v68, v72
	v_add_f32_e32 v246, v69, v73
	v_add_f32_e32 v243, v243, v74
	v_add_f32_e32 v244, v244, v75
	v_add_f32_e32 v245, v245, v76
	v_add_f32_e32 v246, v246, v77
	v_add_f32_e32 v243, v243, v78
	v_add_f32_e32 v244, v244, v79
	v_add_f32_e32 v245, v245, v80
	v_add_f32_e32 v246, v246, v81
	v_add_f32_e32 v243, v243, v82
	v_add_f32_e32 v244, v244, v83
	v_add_f32_e32 v245, v245, v84
	v_add_f32_e32 v246, v246, v85
	v_add_f32_e32 v243, v243, v86
	v_add_f32_e32 v244, v244, v87
	v_add_f32_e32 v245, v245, v88
	v_add_f32_e32 v246, v246, v89
	v_add_f32_e32 v243, v243, v90
	v_add_f32_e32 v244, v244, v91
	v_add_f32_e32 v245, v245, v92
	v_add_f32_e32 v246, v246, v93
	v_add_f32_e32 v243, v243, v94
	v_add_f32_e32 v244, v244, v95
	v_add_f32_e32 v245, v245, v96
	v_add_f32_e32 v246, v246, v97
	v_add_f32_e32 v243, v243, v244
	v_add_f32_e32 v245, v245, v246
	v_add_f32_e32 v243, v243, v245
	v_mov_b32_e32 v236, v195
	v_fma_f32 v237, v237, v248, v243
	v_cvt_pk_bf16_f32 v146, v66, v67
	v_cvt_pk_bf16_f32 v147, v68, v69
	v_cvt_pk_bf16_f32 v148, v70, v71
	v_cvt_pk_bf16_f32 v149, v72, v73
	v_cvt_pk_bf16_f32 v150, v74, v75
	v_cvt_pk_bf16_f32 v151, v76, v77
	v_cvt_pk_bf16_f32 v152, v78, v79
	v_cvt_pk_bf16_f32 v153, v80, v81
	v_cvt_pk_bf16_f32 v154, v82, v83
	v_cvt_pk_bf16_f32 v155, v84, v85
	v_cvt_pk_bf16_f32 v156, v86, v87
	v_cvt_pk_bf16_f32 v157, v88, v89
	v_cvt_pk_bf16_f32 v158, v90, v91
	v_cvt_pk_bf16_f32 v159, v92, v93
	v_cvt_pk_bf16_f32 v160, v94, v95
	v_cvt_pk_bf16_f32 v161, v96, v97

.Lat_f_nobar:
	s_nop 15
	s_nop 7
	s_lshl_b32 s65, s34, 5
	s_cmp_lt_u32 s65, s28
	s_cbranch_scc0 .Lat_e_done
	ds_bpermute_b32 v0, v233, v237
	s_waitcnt lgkmcnt(0)
	v_add_f32_e32 v0, v0, v237
	v_rcp_f32_e32 v247, v0
	v_add_u32_e32 v0, s65, v240
	v_cmp_gt_u32_e32 vcc, s28, v0
	s_and_b64 vcc, vcc, s[2:3]
	s_and_saveexec_b64 s[4:5], vcc
	s_cbranch_execz .Lat_e_restore
	v_add_u32_e32 v0, s38, v234
	v_lshlrev_b32_e32 v0, 11, v0
	v_lshl_add_u32 v0, v241, 3, v0
	s_waitcnt vmcnt(0)
	v_lshlrev_b32_e32 v194, 16, v162
	v_and_b32_e32 v195, 0xffff0000, v162
	v_lshlrev_b32_e32 v196, 16, v163
	v_and_b32_e32 v197, 0xffff0000, v163
	v_mul_f32_e32 v2, v2, v247
	v_mul_f32_e32 v3, v3, v247
	v_mul_f32_e32 v4, v4, v247
	v_mul_f32_e32 v5, v5, v247
	v_mul_f32_e32 v2, v2, v194
	v_mul_f32_e32 v3, v3, v195
	v_mul_f32_e32 v4, v4, v196
	v_mul_f32_e32 v5, v5, v197
	v_cvt_pk_bf16_f32 v66, v2, v3
	v_cvt_pk_bf16_f32 v67, v4, v5
	global_store_dwordx2 v0, v[66:67], s[6:7] offset:0
	v_lshlrev_b32_e32 v194, 16, v164
	v_and_b32_e32 v195, 0xffff0000, v164
	v_lshlrev_b32_e32 v196, 16, v165
	v_and_b32_e32 v197, 0xffff0000, v165
	v_mul_f32_e32 v6, v6, v247
	v_mul_f32_e32 v7, v7, v247
	v_mul_f32_e32 v8, v8, v247
	v_mul_f32_e32 v9, v9, v247
	v_mul_f32_e32 v6, v6, v194
	v_mul_f32_e32 v7, v7, v195
	v_mul_f32_e32 v8, v8, v196
	v_mul_f32_e32 v9, v9, v197
	v_cvt_pk_bf16_f32 v68, v6, v7
	v_cvt_pk_bf16_f32 v69, v8, v9
	global_store_dwordx2 v0, v[68:69], s[6:7] offset:16
	v_lshlrev_b32_e32 v194, 16, v166
	v_and_b32_e32 v195, 0xffff0000, v166
	v_lshlrev_b32_e32 v196, 16, v167
	v_and_b32_e32 v197, 0xffff0000, v167
	v_mul_f32_e32 v10, v10, v247
	v_mul_f32_e32 v11, v11, v247
	v_mul_f32_e32 v12, v12, v247
	v_mul_f32_e32 v13, v13, v247
	v_mul_f32_e32 v10, v10, v194
	v_mul_f32_e32 v11, v11, v195
	v_mul_f32_e32 v12, v12, v196
	v_mul_f32_e32 v13, v13, v197
	v_cvt_pk_bf16_f32 v70, v10, v11
	v_cvt_pk_bf16_f32 v71, v12, v13
	global_store_dwordx2 v0, v[70:71], s[6:7] offset:32
	v_lshlrev_b32_e32 v194, 16, v168
	v_and_b32_e32 v195, 0xffff0000, v168
	v_lshlrev_b32_e32 v196, 16, v169
	v_and_b32_e32 v197, 0xffff0000, v169
	v_mul_f32_e32 v14, v14, v247
	v_mul_f32_e32 v15, v15, v247
	v_mul_f32_e32 v16, v16, v247
	v_mul_f32_e32 v17, v17, v247
	v_mul_f32_e32 v14, v14, v194
	v_mul_f32_e32 v15, v15, v195
	v_mul_f32_e32 v16, v16, v196
	v_mul_f32_e32 v17, v17, v197
	v_cvt_pk_bf16_f32 v72, v14, v15
	v_cvt_pk_bf16_f32 v73, v16, v17
	global_store_dwordx2 v0, v[72:73], s[6:7] offset:48
	v_lshlrev_b32_e32 v194, 16, v170
	v_and_b32_e32 v195, 0xffff0000, v170
	v_lshlrev_b32_e32 v196, 16, v171
	v_and_b32_e32 v197, 0xffff0000, v171
	v_mul_f32_e32 v18, v18, v247
	v_mul_f32_e32 v19, v19, v247
	v_mul_f32_e32 v20, v20, v247
	v_mul_f32_e32 v21, v21, v247
	v_mul_f32_e32 v18, v18, v194
	v_mul_f32_e32 v19, v19, v195
	v_mul_f32_e32 v20, v20, v196
	v_mul_f32_e32 v21, v21, v197
	v_cvt_pk_bf16_f32 v74, v18, v19
	v_cvt_pk_bf16_f32 v75, v20, v21
	global_store_dwordx2 v0, v[74:75], s[6:7] offset:64
	v_lshlrev_b32_e32 v194, 16, v172
	v_and_b32_e32 v195, 0xffff0000, v172
	v_lshlrev_b32_e32 v196, 16, v173
	v_and_b32_e32 v197, 0xffff0000, v173
	v_mul_f32_e32 v22, v22, v247
	v_mul_f32_e32 v23, v23, v247
	v_mul_f32_e32 v24, v24, v247
	v_mul_f32_e32 v25, v25, v247
	v_mul_f32_e32 v22, v22, v194
	v_mul_f32_e32 v23, v23, v195
	v_mul_f32_e32 v24, v24, v196
	v_mul_f32_e32 v25, v25, v197
	v_cvt_pk_bf16_f32 v76, v22, v23
	v_cvt_pk_bf16_f32 v77, v24, v25
	global_store_dwordx2 v0, v[76:77], s[6:7] offset:80
	v_lshlrev_b32_e32 v194, 16, v174
	v_and_b32_e32 v195, 0xffff0000, v174
	v_lshlrev_b32_e32 v196, 16, v175
	v_and_b32_e32 v197, 0xffff0000, v175
	v_mul_f32_e32 v26, v26, v247
	v_mul_f32_e32 v27, v27, v247
	v_mul_f32_e32 v28, v28, v247
	v_mul_f32_e32 v29, v29, v247
	v_mul_f32_e32 v26, v26, v194
	v_mul_f32_e32 v27, v27, v195
	v_mul_f32_e32 v28, v28, v196
	v_mul_f32_e32 v29, v29, v197
	v_cvt_pk_bf16_f32 v78, v26, v27
	v_cvt_pk_bf16_f32 v79, v28, v29
	global_store_dwordx2 v0, v[78:79], s[6:7] offset:96
	v_lshlrev_b32_e32 v194, 16, v176
	v_and_b32_e32 v195, 0xffff0000, v176
	v_lshlrev_b32_e32 v196, 16, v177
	v_and_b32_e32 v197, 0xffff0000, v177
	v_mul_f32_e32 v30, v30, v247
	v_mul_f32_e32 v31, v31, v247
	v_mul_f32_e32 v32, v32, v247
	v_mul_f32_e32 v33, v33, v247
	v_mul_f32_e32 v30, v30, v194
	v_mul_f32_e32 v31, v31, v195
	v_mul_f32_e32 v32, v32, v196
	v_mul_f32_e32 v33, v33, v197
	v_cvt_pk_bf16_f32 v80, v30, v31
	v_cvt_pk_bf16_f32 v81, v32, v33
	global_store_dwordx2 v0, v[80:81], s[6:7] offset:112
	v_lshlrev_b32_e32 v194, 16, v178
	v_and_b32_e32 v195, 0xffff0000, v178
	v_lshlrev_b32_e32 v196, 16, v179
	v_and_b32_e32 v197, 0xffff0000, v179
	v_mul_f32_e32 v34, v34, v247
	v_mul_f32_e32 v35, v35, v247
	v_mul_f32_e32 v36, v36, v247
	v_mul_f32_e32 v37, v37, v247
	v_mul_f32_e32 v34, v34, v194
	v_mul_f32_e32 v35, v35, v195
	v_mul_f32_e32 v36, v36, v196
	v_mul_f32_e32 v37, v37, v197
	v_cvt_pk_bf16_f32 v82, v34, v35
	v_cvt_pk_bf16_f32 v83, v36, v37
	global_store_dwordx2 v0, v[82:83], s[6:7] offset:128
	v_lshlrev_b32_e32 v194, 16, v180
	v_and_b32_e32 v195, 0xffff0000, v180
	v_lshlrev_b32_e32 v196, 16, v181
	v_and_b32_e32 v197, 0xffff0000, v181
	v_mul_f32_e32 v38, v38, v247
	v_mul_f32_e32 v39, v39, v247
	v_mul_f32_e32 v40, v40, v247
	v_mul_f32_e32 v41, v41, v247
	v_mul_f32_e32 v38, v38, v194
	v_mul_f32_e32 v39, v39, v195
	v_mul_f32_e32 v40, v40, v196
	v_mul_f32_e32 v41, v41, v197
	v_cvt_pk_bf16_f32 v84, v38, v39
	v_cvt_pk_bf16_f32 v85, v40, v41
	global_store_dwordx2 v0, v[84:85], s[6:7] offset:144
	v_lshlrev_b32_e32 v194, 16, v182
	v_and_b32_e32 v195, 0xffff0000, v182
	v_lshlrev_b32_e32 v196, 16, v183
	v_and_b32_e32 v197, 0xffff0000, v183
	v_mul_f32_e32 v42, v42, v247
	v_mul_f32_e32 v43, v43, v247
	v_mul_f32_e32 v44, v44, v247
	v_mul_f32_e32 v45, v45, v247
	v_mul_f32_e32 v42, v42, v194
	v_mul_f32_e32 v43, v43, v195
	v_mul_f32_e32 v44, v44, v196
	v_mul_f32_e32 v45, v45, v197
	v_cvt_pk_bf16_f32 v86, v42, v43
	v_cvt_pk_bf16_f32 v87, v44, v45
	global_store_dwordx2 v0, v[86:87], s[6:7] offset:160
	v_lshlrev_b32_e32 v194, 16, v184
	v_and_b32_e32 v195, 0xffff0000, v184
	v_lshlrev_b32_e32 v196, 16, v185
	v_and_b32_e32 v197, 0xffff0000, v185
	v_mul_f32_e32 v46, v46, v247
	v_mul_f32_e32 v47, v47, v247
	v_mul_f32_e32 v48, v48, v247
	v_mul_f32_e32 v49, v49, v247
	v_mul_f32_e32 v46, v46, v194
	v_mul_f32_e32 v47, v47, v195
	v_mul_f32_e32 v48, v48, v196
	v_mul_f32_e32 v49, v49, v197
	v_cvt_pk_bf16_f32 v88, v46, v47
	v_cvt_pk_bf16_f32 v89, v48, v49
	global_store_dwordx2 v0, v[88:89], s[6:7] offset:176
	v_lshlrev_b32_e32 v194, 16, v186
	v_and_b32_e32 v195, 0xffff0000, v186
	v_lshlrev_b32_e32 v196, 16, v187
	v_and_b32_e32 v197, 0xffff0000, v187
	v_mul_f32_e32 v50, v50, v247
	v_mul_f32_e32 v51, v51, v247
	v_mul_f32_e32 v52, v52, v247
	v_mul_f32_e32 v53, v53, v247
	v_mul_f32_e32 v50, v50, v194
	v_mul_f32_e32 v51, v51, v195
	v_mul_f32_e32 v52, v52, v196
	v_mul_f32_e32 v53, v53, v197
	v_cvt_pk_bf16_f32 v90, v50, v51
	v_cvt_pk_bf16_f32 v91, v52, v53
	global_store_dwordx2 v0, v[90:91], s[6:7] offset:192
	v_lshlrev_b32_e32 v194, 16, v188
	v_and_b32_e32 v195, 0xffff0000, v188
	v_lshlrev_b32_e32 v196, 16, v189
	v_and_b32_e32 v197, 0xffff0000, v189
	v_mul_f32_e32 v54, v54, v247
	v_mul_f32_e32 v55, v55, v247
	v_mul_f32_e32 v56, v56, v247
	v_mul_f32_e32 v57, v57, v247
	v_mul_f32_e32 v54, v54, v194
	v_mul_f32_e32 v55, v55, v195
	v_mul_f32_e32 v56, v56, v196
	v_mul_f32_e32 v57, v57, v197
	v_cvt_pk_bf16_f32 v92, v54, v55
	v_cvt_pk_bf16_f32 v93, v56, v57
	global_store_dwordx2 v0, v[92:93], s[6:7] offset:208
	v_lshlrev_b32_e32 v194, 16, v190
	v_and_b32_e32 v195, 0xffff0000, v190
	v_lshlrev_b32_e32 v196, 16, v191
	v_and_b32_e32 v197, 0xffff0000, v191
	v_mul_f32_e32 v58, v58, v247
	v_mul_f32_e32 v59, v59, v247
	v_mul_f32_e32 v60, v60, v247
	v_mul_f32_e32 v61, v61, v247
	v_mul_f32_e32 v58, v58, v194
	v_mul_f32_e32 v59, v59, v195
	v_mul_f32_e32 v60, v60, v196
	v_mul_f32_e32 v61, v61, v197
	v_cvt_pk_bf16_f32 v94, v58, v59
	v_cvt_pk_bf16_f32 v95, v60, v61
	global_store_dwordx2 v0, v[94:95], s[6:7] offset:224
	v_lshlrev_b32_e32 v194, 16, v192
	v_and_b32_e32 v195, 0xffff0000, v192
	v_lshlrev_b32_e32 v196, 16, v193
	v_and_b32_e32 v197, 0xffff0000, v193
	v_mul_f32_e32 v62, v62, v247
	v_mul_f32_e32 v63, v63, v247
	v_mul_f32_e32 v64, v64, v247
	v_mul_f32_e32 v65, v65, v247
	v_mul_f32_e32 v62, v62, v194
	v_mul_f32_e32 v63, v63, v195
	v_mul_f32_e32 v64, v64, v196
	v_mul_f32_e32 v65, v65, v197
	v_cvt_pk_bf16_f32 v96, v62, v63
	v_cvt_pk_bf16_f32 v97, v64, v65
	global_store_dwordx2 v0, v[96:97], s[6:7] offset:240
